# layer-0 up-projection weight transposes split between the phase-2 hook (items 2048-3455) and phase 4's idle workgroups (items 3456-4863), shared copied loop
# baseline (speedup 1.0000x reference)
.LBB0_808:
	s_cmp_lg_u32 s55, 4
	s_cbranch_scc1 .Ltq_ret4
	s_cmpk_lg_u32 s24, 0x100
	s_cbranch_scc1 .Ltq_ret4
	v_readlane_b32 s98, v255, 6
	s_nop 3
	s_cmp_lt_u32 s98, 192
	s_cbranch_scc1 .Ltq_ret4
	s_waitcnt vmcnt(0) lgkmcnt(0)
	s_barrier
	v_writelane_b32 v255, s0, 24
	v_writelane_b32 v255, s1, 25
	v_writelane_b32 v255, s2, 26
	v_writelane_b32 v255, s3, 27
	v_writelane_b32 v255, s20, 28
	v_writelane_b32 v255, s21, 29
	v_writelane_b32 v255, s22, 30
	v_writelane_b32 v255, s23, 31
	v_writelane_b32 v255, s26, 32
	v_writelane_b32 v255, s33, 33
	v_writelane_b32 v255, s34, 34
	v_writelane_b32 v255, s35, 35
	v_writelane_b32 v255, s36, 36
	v_writelane_b32 v255, s37, 37
	v_writelane_b32 v255, s38, 38
	v_writelane_b32 v255, s39, 39
	v_writelane_b32 v255, s40, 40
	v_writelane_b32 v255, s41, 41
	v_writelane_b32 v255, s42, 42
	v_writelane_b32 v255, s43, 43
	v_writelane_b32 v255, s56, 44
	v_writelane_b32 v255, s57, 45
	v_writelane_b32 v255, s58, 46
	v_writelane_b32 v255, s60, 47
	v_writelane_b32 v255, s61, 48
	v_writelane_b32 v255, s80, 49
	v_writelane_b32 v255, s81, 50
	v_writelane_b32 v255, s82, 51
	v_writelane_b32 v255, s83, 52
	v_writelane_b32 v255, s86, 53
	v_writelane_b32 v255, s87, 54
	v_writelane_b32 v255, s88, 55
	v_writelane_b32 v255, s89, 56
	v_writelane_b32 v255, s90, 57
	v_writelane_b32 v255, s91, 58
	v_writelane_b32 v255, s92, 59
	v_writelane_b32 v255, s93, 60
	v_writelane_b32 v255, s94, 61
	v_writelane_b32 v255, s95, 62
	v_readlane_b32 s1, v255, 5
	s_nop 3
	s_sub_i32 s0, s98, 192
	s_lshl_b32 s0, s0, 3
	s_add_i32 s2, s1, s0
	s_addk_i32 s2, 0xd80
	s_movk_i32 s20, 0x200
	s_mov_b32 s27, 0
	s_movk_i32 s99, 0x1300
	s_branch .Ltq_body

.LBB0_1147:
	s_waitcnt vmcnt(0)
	s_cmp_lg_u32 s55, 2
	s_cbranch_scc1 .Ltq_skip
	s_cmpk_lg_u32 s24, 0x100
	s_cbranch_scc1 .Ltq_skip
	v_readlane_b32 s98, v255, 6
	s_nop 3
	s_cmp_lt_u32 s98, 64
	s_cbranch_scc1 .Ltq_skip
	s_barrier
	v_writelane_b32 v255, s0, 24
	v_writelane_b32 v255, s1, 25
	v_writelane_b32 v255, s2, 26
	v_writelane_b32 v255, s3, 27
	v_writelane_b32 v255, s20, 28
	v_writelane_b32 v255, s21, 29
	v_writelane_b32 v255, s22, 30
	v_writelane_b32 v255, s23, 31
	v_writelane_b32 v255, s26, 32
	v_writelane_b32 v255, s33, 33
	v_writelane_b32 v255, s34, 34
	v_writelane_b32 v255, s35, 35
	v_writelane_b32 v255, s36, 36
	v_writelane_b32 v255, s37, 37
	v_writelane_b32 v255, s38, 38
	v_writelane_b32 v255, s39, 39
	v_writelane_b32 v255, s40, 40
	v_writelane_b32 v255, s41, 41
	v_writelane_b32 v255, s42, 42
	v_writelane_b32 v255, s43, 43
	v_writelane_b32 v255, s56, 44
	v_writelane_b32 v255, s57, 45
	v_writelane_b32 v255, s58, 46
	v_writelane_b32 v255, s60, 47
	v_writelane_b32 v255, s61, 48
	v_writelane_b32 v255, s80, 49
	v_writelane_b32 v255, s81, 50
	v_writelane_b32 v255, s82, 51
	v_writelane_b32 v255, s83, 52
	v_writelane_b32 v255, s86, 53
	v_writelane_b32 v255, s87, 54
	v_writelane_b32 v255, s88, 55
	v_writelane_b32 v255, s89, 56
	v_writelane_b32 v255, s90, 57
	v_writelane_b32 v255, s91, 58
	v_writelane_b32 v255, s92, 59
	v_writelane_b32 v255, s93, 60
	v_writelane_b32 v255, s94, 61
	v_writelane_b32 v255, s95, 62
	s_movk_i32 s99, 0xd80
	v_readlane_b32 s1, v255, 5
	s_nop 3
	s_sub_i32 s0, s98, 64
	s_lshl_b32 s0, s0, 3
	s_add_i32 s2, s1, s0
	s_addk_i32 s2, 0x800
	s_movk_i32 s20, 0x600
	s_mov_b32 s27, 0
	s_cmp_ge_i32 s2, s99
	s_cbranch_scc1 .Ltq_exit2
.Ltq_body:
	v_and_b32_e32 v44, 63, v192
	v_lshrrev_b32_e32 v44, 3, v44
	s_lshl_b32 s0, s1, 14
	v_and_b32_e32 v0, 7, v192
	s_add_i32 s0, s0, 0
	v_lshlrev_b32_e32 v178, 4, v0
	v_mul_u32_u24_e32 v0, 0x420, v0
	v_lshlrev_b32_e32 v1, 2, v44
	v_add_u32_e32 v12, s0, v178
	v_add3_u32 v17, s0, v0, v1
	v_readlane_b32 s0, v253, 6
	v_readlane_b32 s1, v253, 7
	s_mov_b64 s[60:61], s[84:85]
	v_readlane_b32 s80, v253, 46
	v_lshl_add_u64 v[0:1], s[0:1], 0, v[178:179]
	v_readlane_b32 s0, v254, 18
	v_readlane_b32 s1, v254, 19
	v_readlane_b32 s84, v253, 50
	v_readlane_b32 s85, v253, 51
	v_lshl_add_u64 v[2:3], s[0:1], 0, v[178:179]
	v_readlane_b32 s90, v253, 56
	v_readlane_b32 s91, v253, 57
	s_lshl_b32 s0, s2, 1
	v_mul_u32_u24_e32 v13, 0x84, v44
	v_or_b32_e32 v14, 8, v44
	v_or_b32_e32 v15, 16, v44
	v_or_b32_e32 v16, 24, v44
	v_lshl_add_u64 v[4:5], s[78:79], 0, v[178:179]
	v_lshl_add_u64 v[6:7], s[66:67], 0, v[178:179]
	v_lshl_add_u64 v[8:9], s[90:91], 0, v[178:179]
	v_lshl_add_u64 v[10:11], s[84:85], 0, v[178:179]
	s_lshl_b32 s3, s2, 5
	s_lshl_b32 s21, s20, 5
	s_add_i32 s33, s0, 0x1f400
	s_lshl_b32 s34, s20, 1
	s_mov_b32 s35, s2
	s_mov_b32 s38, 0x10000
	s_movk_i32 s39, 0x3000
	s_mov_b32 s40, 0x2c000
	s_mov_b32 s41, 0x58000
	s_mov_b32 s42, 0x84000
	s_mov_b32 s43, 0xb0000
	s_mov_b32 s56, 0xdc000
	s_mov_b32 s57, 0x108000
	s_mov_b32 s58, 0x134000
	v_readlane_b32 s81, v253, 47
	v_readlane_b32 s82, v253, 48
	v_readlane_b32 s83, v253, 49
	v_readlane_b32 s86, v253, 52
	v_readlane_b32 s87, v253, 53
	v_readlane_b32 s88, v253, 54
	v_readlane_b32 s89, v253, 55
	v_readlane_b32 s92, v253, 58
	v_readlane_b32 s93, v253, 59
	v_readlane_b32 s94, v253, 60
	v_readlane_b32 s95, v253, 61
	s_branch .Ltq_1116

.Ltq_exit2:
	v_readlane_b32 s0, v255, 24
	v_readlane_b32 s1, v255, 25
	v_readlane_b32 s2, v255, 26
	v_readlane_b32 s3, v255, 27
	v_readlane_b32 s20, v255, 28
	v_readlane_b32 s21, v255, 29
	v_readlane_b32 s22, v255, 30
	v_readlane_b32 s23, v255, 31
	v_readlane_b32 s26, v255, 32
	v_readlane_b32 s33, v255, 33
	v_readlane_b32 s34, v255, 34
	v_readlane_b32 s35, v255, 35
	v_readlane_b32 s36, v255, 36
	v_readlane_b32 s37, v255, 37
	v_readlane_b32 s38, v255, 38
	v_readlane_b32 s39, v255, 39
	v_readlane_b32 s40, v255, 40
	v_readlane_b32 s41, v255, 41
	v_readlane_b32 s42, v255, 42
	v_readlane_b32 s43, v255, 43
	v_readlane_b32 s56, v255, 44
	v_readlane_b32 s57, v255, 45
	v_readlane_b32 s58, v255, 46
	v_readlane_b32 s60, v255, 47
	v_readlane_b32 s61, v255, 48
	v_readlane_b32 s80, v255, 49
	v_readlane_b32 s81, v255, 50
	v_readlane_b32 s82, v255, 51
	v_readlane_b32 s83, v255, 52
	v_readlane_b32 s86, v255, 53
	v_readlane_b32 s87, v255, 54
	v_readlane_b32 s88, v255, 55
	v_readlane_b32 s89, v255, 56
	v_readlane_b32 s90, v255, 57
	v_readlane_b32 s91, v255, 58
	v_readlane_b32 s92, v255, 59
	v_readlane_b32 s93, v255, 60
	v_readlane_b32 s94, v255, 61
	v_readlane_b32 s95, v255, 62
	s_nop 4
	s_cmp_eq_u32 s55, 4
	s_cbranch_scc1 .Ltq_ret4
	s_barrier
	v_writelane_b32 v255, s0, 24
	v_writelane_b32 v255, s1, 25
	v_writelane_b32 v255, s2, 26
	v_writelane_b32 v255, s3, 27
	v_writelane_b32 v255, s20, 28
	v_writelane_b32 v255, s21, 29
	v_writelane_b32 v255, s22, 30
	v_writelane_b32 v255, s23, 31
	v_writelane_b32 v255, s26, 32
	v_writelane_b32 v255, s34, 33
	v_writelane_b32 v255, s35, 34
	v_writelane_b32 v255, s36, 35
	v_writelane_b32 v255, s37, 36
	v_writelane_b32 v255, s38, 37
	v_writelane_b32 v255, s39, 38
	v_writelane_b32 v255, s40, 39
	v_writelane_b32 v255, s41, 40
	v_writelane_b32 v255, s44, 41
	v_writelane_b32 v255, s45, 42
	v_writelane_b32 v255, s56, 43
	v_readlane_b32 s56, v255, 6
	s_nop 3
	s_movk_i32 s0, 0x1400
	v_cmp_gt_i32_e32 vcc, s0, v192
	s_and_saveexec_b64 s[0:1], vcc
	v_readlane_b32 s44, v254, 34
	s_movk_i32 s26, 0x3ff
	v_readlane_b32 s45, v254, 35
	s_cbranch_execz .Lal_1101

	v_lshl_add_u32 v2, v192, 2, 0
	s_mov_b64 s[2:3], 0
	v_mov_b32_e32 v3, v192
	s_branch .Lal_1097
